# v03: + window-buffer copy 5 loads in flight (was load-wait-store per 16B), adaLN partial-sum reduce as one float4 round trip per lane
# baseline (speedup 1.0000x reference)
.LBB0_226:
	s_cmp_lt_i32 s96, 2
	s_cselect_b64 s[2:3], -1, 0
	s_and_b64 s[0:1], s[2:3], s[0:1]
	s_andn2_b64 vcc, exec, s[0:1]
	s_cbranch_vccnz .LBB0_231
	s_lshl_b32 s0, s94, 9
	s_and_b32 s1, s87, 0xffffffc0
	v_mbcnt_hi_u32_b32 v0, -1, v216
	s_add_i32 s1, s1, s0
	v_add_u32_e32 v0, s1, v0
	s_mov_b32 s0, 0x19800
	v_cmp_gt_i32_e32 vcc, s0, v0
	s_and_saveexec_b64 s[0:1], vcc
	s_cbranch_execz .LBB0_230
	v_lshlrev_b32_e32 v1, 4, v0
	s_add_u32 s4, s90, 0x478d1600
	s_addc_u32 s5, s91, 0
	s_add_u32 s6, s90, 0x7b03600
	s_addc_u32 s7, s91, 0
	s_mov_b32 s8, 0x55555556
	global_load_dwordx4 v[4:7], v1, s[4:5]
	v_add_u32_e32 v2, 0x198000, v1
	global_load_dwordx4 v[8:11], v2, s[4:5]
	v_add_u32_e32 v2, 0x198000, v2
	global_load_dwordx4 v[12:15], v2, s[4:5]
	v_add_u32_e32 v2, 0x198000, v2
	global_load_dwordx4 v[16:19], v2, s[4:5]
	v_add_u32_e32 v2, 0x198000, v2
	global_load_dwordx4 v[20:23], v2, s[4:5]
	v_add_u32_e32 v2, 0x198000, v2
	global_load_dwordx4 v[24:27], v2, s[4:5]
	v_add_u32_e32 v2, 0x198000, v2
	global_load_dwordx4 v[28:31], v2, s[4:5]
	v_add_u32_e32 v2, 0x198000, v2
	global_load_dwordx4 v[32:35], v2, s[4:5]
	v_lshlrev_b32_e32 v3, 2, v0
	v_lshrrev_b32_e32 v36, 12, v3
	v_mul_hi_u32 v36, v36, s8
	v_mul_u32_u24_e32 v36, 0x3000, v36
	v_sub_u32_e32 v36, v3, v36
	v_lshlrev_b32_e32 v36, 2, v36
	global_load_dwordx4 v[36:39], v36, s[72:73]
	s_waitcnt vmcnt(0)
	v_add_f32_e32 v36, v36, v4
	v_add_f32_e32 v37, v37, v5
	v_add_f32_e32 v38, v38, v6
	v_add_f32_e32 v39, v39, v7
	v_add_f32_e32 v36, v36, v8
	v_add_f32_e32 v37, v37, v9
	v_add_f32_e32 v38, v38, v10
	v_add_f32_e32 v39, v39, v11
	v_add_f32_e32 v36, v36, v12
	v_add_f32_e32 v37, v37, v13
	v_add_f32_e32 v38, v38, v14
	v_add_f32_e32 v39, v39, v15
	v_add_f32_e32 v36, v36, v16
	v_add_f32_e32 v37, v37, v17
	v_add_f32_e32 v38, v38, v18
	v_add_f32_e32 v39, v39, v19
	v_add_f32_e32 v36, v36, v20
	v_add_f32_e32 v37, v37, v21
	v_add_f32_e32 v38, v38, v22
	v_add_f32_e32 v39, v39, v23
	v_add_f32_e32 v36, v36, v24
	v_add_f32_e32 v37, v37, v25
	v_add_f32_e32 v38, v38, v26
	v_add_f32_e32 v39, v39, v27
	v_add_f32_e32 v36, v36, v28
	v_add_f32_e32 v37, v37, v29
	v_add_f32_e32 v38, v38, v30
	v_add_f32_e32 v39, v39, v31
	v_add_f32_e32 v36, v36, v32
	v_add_f32_e32 v37, v37, v33
	v_add_f32_e32 v38, v38, v34
	v_add_f32_e32 v39, v39, v35
	global_store_dwordx4 v1, v[36:39], s[6:7]

.LBB0_947:
	s_ashr_i32 s95, s94, 31
	s_lshl_b64 s[0:1], s[94:95], 9
	v_lshl_add_u64 v[0:1], s[0:1], 0, v[64:65]
	s_mov_b64 s[0:1], 0x1f8000
	v_cmp_gt_u64_e32 vcc, s[0:1], v[0:1]
	s_and_saveexec_b64 s[0:1], vcc
	v_readlane_b32 s8, v239, 3
	v_readlane_b32 s20, v239, 15
	v_readlane_b32 s21, v239, 16
	v_readlane_b32 s9, v239, 4
	v_readlane_b32 s10, v239, 5
	v_readlane_b32 s11, v239, 6
	v_readlane_b32 s12, v239, 7
	v_readlane_b32 s13, v239, 8
	v_readlane_b32 s14, v239, 9
	v_readlane_b32 s15, v239, 10
	v_readlane_b32 s16, v239, 11
	v_readlane_b32 s17, v239, 12
	v_readlane_b32 s18, v239, 13
	v_readlane_b32 s19, v239, 14
	v_readlane_b32 s22, v239, 17
	v_readlane_b32 s23, v239, 18
	s_cbranch_execz .LBB0_950
	s_add_u32 s4, s88, 0x6500000
	s_addc_u32 s5, s89, 0
	s_add_u32 s8, s20, 0x4000
	s_addc_u32 s9, s21, 0
	s_lshl_b32 s6, s92, 9
	s_mov_b32 s12, 0x4104105
	s_lshl_b32 s7, s6, 2
	s_sub_i32 s10, 0x1f8000, s7
	s_mov_b32 s11, 0x1f8000
.Lwc_group:
	v_cmp_gt_i32_e32 vcc, s10, v0
	s_cmp_eq_u64 vcc, exec
	s_cbranch_scc0 .Lwc_tail
	v_lshrrev_b32_e32 v2, 10, v0
	v_mul_hi_u32 v2, v2, s12
	v_mul_u32_u24_e32 v3, 0xfc00, v2
	v_sub_u32_e32 v3, v0, v3
	v_lshlrev_b32_e32 v3, 4, v3
	v_lshl_add_u32 v10, v2, 20, v3
	global_load_dwordx4 v[16:19], v10, s[8:9]
	v_add_u32_e32 v4, s6, v0
	v_lshrrev_b32_e32 v2, 10, v4
	v_mul_hi_u32 v2, v2, s12
	v_mul_u32_u24_e32 v3, 0xfc00, v2
	v_sub_u32_e32 v3, v4, v3
	v_lshlrev_b32_e32 v3, 4, v3
	v_lshl_add_u32 v11, v2, 20, v3
	global_load_dwordx4 v[20:23], v11, s[8:9]
	v_add_u32_e32 v4, s6, v4
	v_lshrrev_b32_e32 v2, 10, v4
	v_mul_hi_u32 v2, v2, s12
	v_mul_u32_u24_e32 v3, 0xfc00, v2
	v_sub_u32_e32 v3, v4, v3
	v_lshlrev_b32_e32 v3, 4, v3
	v_lshl_add_u32 v12, v2, 20, v3
	global_load_dwordx4 v[24:27], v12, s[8:9]
	v_add_u32_e32 v4, s6, v4
	v_lshrrev_b32_e32 v2, 10, v4
	v_mul_hi_u32 v2, v2, s12
	v_mul_u32_u24_e32 v3, 0xfc00, v2
	v_sub_u32_e32 v3, v4, v3
	v_lshlrev_b32_e32 v3, 4, v3
	v_lshl_add_u32 v13, v2, 20, v3
	global_load_dwordx4 v[28:31], v13, s[8:9]
	v_add_u32_e32 v4, s6, v4
	v_lshrrev_b32_e32 v2, 10, v4
	v_mul_hi_u32 v2, v2, s12
	v_mul_u32_u24_e32 v3, 0xfc00, v2
	v_sub_u32_e32 v3, v4, v3
	v_lshlrev_b32_e32 v3, 4, v3
	v_lshl_add_u32 v14, v2, 20, v3
	global_load_dwordx4 v[32:35], v14, s[8:9]
	v_add_u32_e32 v0, s6, v4
	s_waitcnt vmcnt(4)
	global_store_dwordx4 v10, v[16:19], s[4:5]
	s_waitcnt vmcnt(4)
	global_store_dwordx4 v11, v[20:23], s[4:5]
	s_waitcnt vmcnt(4)
	global_store_dwordx4 v12, v[24:27], s[4:5]
	s_waitcnt vmcnt(4)
	global_store_dwordx4 v13, v[28:31], s[4:5]
	s_waitcnt vmcnt(4)
	global_store_dwordx4 v14, v[32:35], s[4:5]
	s_branch .Lwc_group
.Lwc_tail:
	v_cmp_gt_u32_e32 vcc, s11, v0
	s_and_b64 exec, exec, vcc
	s_cbranch_execz .LBB0_950
.Lwc_tail_loop:
	v_lshrrev_b32_e32 v2, 10, v0
	v_mul_hi_u32 v2, v2, s12
	v_mul_u32_u24_e32 v3, 0xfc00, v2
	v_sub_u32_e32 v3, v0, v3
	v_lshlrev_b32_e32 v3, 4, v3
	v_lshl_add_u32 v10, v2, 20, v3
	global_load_dwordx4 v[16:19], v10, s[8:9]
	v_add_u32_e32 v0, s6, v0
	v_cmp_gt_u32_e32 vcc, s11, v0
	s_waitcnt vmcnt(0)
	global_store_dwordx4 v10, v[16:19], s[4:5]
	s_and_b64 exec, exec, vcc
	s_cbranch_execnz .Lwc_tail_loop
